# rwkv_post: next token's 20 lines touched early (replica of the address code, scratch loads behind the current token's loads); counted waits +20
# baseline (speedup 1.0000x reference)
.LBB0_1148:
	s_ashr_i32 s4, s2, 2
	s_ashr_i32 s5, s2, 31
	s_lshr_b32 s6, s5, 19
	s_ashr_i32 s5, s4, 31
	s_add_i32 s8, s4, s6
	s_lshl_b64 s[6:7], s[4:5], 8
	v_mov_b32_e32 v29, s7
	v_or_b32_e32 v28, s6, v0
	s_and_b32 s20, s4, 0x1fff
	s_lshl_b64 s[4:5], s[4:5], 11
	s_ashr_i32 s8, s8, 13
	v_mov_b32_e32 v31, s7
	v_or_b32_e32 v30, s6, v2
	v_mov_b32_e32 v33, s7
	v_or_b32_e32 v32, s6, v4
	v_mov_b32_e32 v35, s7
	v_or_b32_e32 v34, s6, v6
	v_lshl_add_u64 v[36:37], v[28:29], 2, s[12:13]
	v_lshl_add_u64 v[14:15], v[10:11], 0, s[4:5]
	s_lshl_b32 s4, s8, 2
	v_lshl_add_u64 v[28:29], v[28:29], 1, s[14:15]
	v_lshl_add_u64 v[38:39], v[30:31], 2, s[12:13]
	v_lshl_add_u64 v[30:31], v[30:31], 1, s[14:15]
	v_lshl_add_u64 v[40:41], v[32:33], 2, s[12:13]
	v_lshl_add_u64 v[32:33], v[32:33], 1, s[14:15]
	v_lshl_add_u64 v[42:43], v[34:35], 2, s[12:13]
	v_lshl_add_u64 v[34:35], v[34:35], 1, s[14:15]
	global_load_dword v45, v[36:37], off
	global_load_ushort v27, v[28:29], off
	global_load_dword v44, v[38:39], off
	global_load_ushort v48, v[30:31], off
	global_load_dword v47, v[40:41], off
	global_load_ushort v49, v[32:33], off
	global_load_dword v46, v[42:43], off
	global_load_ushort v50, v[34:35], off
	s_ashr_i32 s5, s4, 31
	s_or_b32 s6, s4, 1
	s_or_b32 s8, s4, 2
	s_or_b32 s18, s4, 3
	s_lshl_b64 s[4:5], s[4:5], 13
	s_ashr_i32 s7, s6, 31
	s_ashr_i32 s9, s8, 31
	s_ashr_i32 s19, s18, 31
	s_or_b32 s21, s4, s20
	s_mul_i32 s22, s5, 0x380
	s_lshl_b64 s[4:5], s[6:7], 13
	s_lshl_b64 s[6:7], s[8:9], 13
	s_lshl_b64 s[8:9], s[18:19], 13
	v_mad_u64_u32 v[28:29], s[18:19], s21, v26, v[8:9]
	v_add_u32_e32 v29, s22, v29
	global_load_ushort v36, v[28:29], off offset:256
	global_load_ushort v37, v[28:29], off offset:384
	global_load_ushort v40, v[28:29], off offset:512
	s_or_b32 s4, s4, s20
	s_mul_i32 s18, s5, 0x380
	s_or_b32 s6, s6, s20
	s_or_b32 s8, s8, s20
	v_mad_u64_u32 v[30:31], s[4:5], s4, v26, v[8:9]
	s_mulk_i32 s7, 0x380
	s_mulk_i32 s9, 0x380
	v_mad_u64_u32 v[32:33], s[4:5], s6, v26, v[8:9]
	v_mad_u64_u32 v[34:35], s[4:5], s8, v26, v[8:9]
	v_add_u32_e32 v31, s18, v31
	v_add_u32_e32 v33, s7, v33
	v_add_u32_e32 v35, s9, v35
	global_load_ushort v38, v[30:31], off offset:256
	global_load_ushort v39, v[30:31], off offset:384
	global_load_ushort v41, v[32:33], off offset:256
	global_load_ushort v42, v[32:33], off offset:384
	global_load_ushort v43, v[34:35], off offset:256
	global_load_ushort v51, v[34:35], off offset:384
	global_load_ushort v52, v[30:31], off offset:512
	global_load_ushort v53, v[32:33], off offset:512
	global_load_ushort v54, v[34:35], off offset:512
	s_add_i32 s35, s2, s1
	s_cmp_lt_i32 s35, 0x10000
	s_cselect_b32 s35, s35, s2
	s_ashr_i32 s24, s35, 2
	s_ashr_i32 s25, s35, 31
	s_lshr_b32 s26, s25, 19
	s_ashr_i32 s25, s24, 31
	s_add_i32 s28, s24, s26
	s_lshl_b64 s[26:27], s[24:25], 8
	v_mov_b32_e32 v61, s27
	v_or_b32_e32 v60, s26, v0
	s_and_b32 s32, s24, 0x1fff
	s_lshl_b64 s[24:25], s[24:25], 11
	s_ashr_i32 s28, s28, 13
	v_mov_b32_e32 v63, s27
	v_or_b32_e32 v62, s26, v2
	v_mov_b32_e32 v65, s27
	v_or_b32_e32 v64, s26, v4
	v_mov_b32_e32 v67, s27
	v_or_b32_e32 v66, s26, v6
	v_lshl_add_u64 v[68:69], v[60:61], 2, s[12:13]
	s_lshl_b32 s24, s28, 2
	v_lshl_add_u64 v[60:61], v[60:61], 1, s[14:15]
	v_lshl_add_u64 v[70:71], v[62:63], 2, s[12:13]
	v_lshl_add_u64 v[62:63], v[62:63], 1, s[14:15]
	v_lshl_add_u64 v[72:73], v[64:65], 2, s[12:13]
	v_lshl_add_u64 v[64:65], v[64:65], 1, s[14:15]
	v_lshl_add_u64 v[74:75], v[66:67], 2, s[12:13]
	v_lshl_add_u64 v[66:67], v[66:67], 1, s[14:15]
	global_load_dword v76, v[68:69], off
	global_load_ushort v76, v[60:61], off
	global_load_dword v76, v[70:71], off
	global_load_ushort v76, v[62:63], off
	global_load_dword v76, v[72:73], off
	global_load_ushort v76, v[64:65], off
	global_load_dword v76, v[74:75], off
	global_load_ushort v76, v[66:67], off
	s_ashr_i32 s25, s24, 31
	s_or_b32 s26, s24, 1
	s_or_b32 s28, s24, 2
	s_or_b32 s30, s24, 3
	s_lshl_b64 s[24:25], s[24:25], 13
	s_ashr_i32 s27, s26, 31
	s_ashr_i32 s29, s28, 31
	s_ashr_i32 s31, s30, 31
	s_or_b32 s33, s24, s32
	s_mul_i32 s34, s25, 0x380
	s_lshl_b64 s[24:25], s[26:27], 13
	s_lshl_b64 s[26:27], s[28:29], 13
	s_lshl_b64 s[28:29], s[30:31], 13
	v_mad_u64_u32 v[60:61], s[30:31], s33, v26, v[8:9]
	v_add_u32_e32 v61, s34, v61
	global_load_ushort v76, v[60:61], off offset:256
	global_load_ushort v76, v[60:61], off offset:384
	global_load_ushort v76, v[60:61], off offset:512
	s_or_b32 s24, s24, s32
	s_mul_i32 s30, s25, 0x380
	s_or_b32 s26, s26, s32
	s_or_b32 s28, s28, s32
	v_mad_u64_u32 v[62:63], s[24:25], s24, v26, v[8:9]
	s_mulk_i32 s27, 0x380
	s_mulk_i32 s29, 0x380
	v_mad_u64_u32 v[64:65], s[24:25], s26, v26, v[8:9]
	v_mad_u64_u32 v[66:67], s[24:25], s28, v26, v[8:9]
	v_add_u32_e32 v63, s30, v63
	v_add_u32_e32 v65, s27, v65
	v_add_u32_e32 v67, s29, v67
	global_load_ushort v76, v[62:63], off offset:256
	global_load_ushort v76, v[62:63], off offset:384
	global_load_ushort v76, v[64:65], off offset:256
	global_load_ushort v76, v[64:65], off offset:384
	global_load_ushort v76, v[66:67], off offset:256
	global_load_ushort v76, v[66:67], off offset:384
	global_load_ushort v76, v[62:63], off offset:512
	global_load_ushort v76, v[64:65], off offset:512
	global_load_ushort v76, v[66:67], off offset:512
	s_add_i32 s2, s2, s1
	s_cmp_lt_i32 s2, 0x10000
	s_waitcnt vmcnt(39)
	v_mov_b32_dpp v29, v45 quad_perm:[1,0,3,2] row_mask:0xf bank_mask:0xf bound_ctrl:1
	s_waitcnt vmcnt(38)
	v_cvt_f32_f16_e32 v27, v27
	s_waitcnt vmcnt(37)
	v_mov_b32_dpp v28, v44 quad_perm:[1,0,3,2] row_mask:0xf bank_mask:0xf bound_ctrl:1
	v_pk_add_f32 v[28:29], v[44:45], v[28:29]
	s_waitcnt vmcnt(35)
	v_mov_b32_dpp v31, v47 quad_perm:[1,0,3,2] row_mask:0xf bank_mask:0xf bound_ctrl:1
	v_cvt_f32_f16_e32 v48, v48
	s_waitcnt vmcnt(33)
	v_mov_b32_dpp v30, v46 quad_perm:[1,0,3,2] row_mask:0xf bank_mask:0xf bound_ctrl:1
	v_pk_add_f32 v[30:31], v[46:47], v[30:31]
	v_mov_b32_dpp v33, v29 quad_perm:[2,3,0,1] row_mask:0xf bank_mask:0xf bound_ctrl:1
	v_mov_b32_dpp v32, v28 quad_perm:[2,3,0,1] row_mask:0xf bank_mask:0xf bound_ctrl:1
	v_mov_b32_dpp v35, v31 quad_perm:[2,3,0,1] row_mask:0xf bank_mask:0xf bound_ctrl:1
	v_mov_b32_dpp v34, v30 quad_perm:[2,3,0,1] row_mask:0xf bank_mask:0xf bound_ctrl:1
	v_pk_add_f32 v[28:29], v[28:29], v[32:33]
	v_pk_add_f32 v[30:31], v[30:31], v[34:35]
	v_cvt_f32_f16_e32 v49, v49
	v_mov_b32_dpp v33, v29 row_half_mirror row_mask:0xf bank_mask:0xf bound_ctrl:1
	v_mov_b32_dpp v32, v28 row_half_mirror row_mask:0xf bank_mask:0xf bound_ctrl:1
	v_mov_b32_dpp v35, v31 row_half_mirror row_mask:0xf bank_mask:0xf bound_ctrl:1
	v_mov_b32_dpp v34, v30 row_half_mirror row_mask:0xf bank_mask:0xf bound_ctrl:1
	v_pk_add_f32 v[28:29], v[28:29], v[32:33]
	v_pk_add_f32 v[30:31], v[30:31], v[34:35]
	s_waitcnt vmcnt(32)
	v_cvt_f32_f16_e32 v50, v50
	v_mov_b32_dpp v33, v29 row_mirror row_mask:0xf bank_mask:0xf bound_ctrl:1
	v_mov_b32_dpp v32, v28 row_mirror row_mask:0xf bank_mask:0xf bound_ctrl:1
	s_waitcnt vmcnt(31)
	v_cvt_f32_f16_e32 v36, v36
	s_waitcnt vmcnt(30)
	v_cvt_f32_f16_e32 v37, v37
	v_mov_b32_dpp v35, v31 row_mirror row_mask:0xf bank_mask:0xf bound_ctrl:1
	v_mov_b32_dpp v34, v30 row_mirror row_mask:0xf bank_mask:0xf bound_ctrl:1
	v_pk_add_f32 v[28:29], v[28:29], v[32:33]
	v_pk_add_f32 v[30:31], v[30:31], v[34:35]
	ds_bpermute_b32 v33, v24, v29
	ds_bpermute_b32 v32, v24, v28
	s_waitcnt vmcnt(28)
	v_cvt_f32_f16_e32 v38, v38
	s_waitcnt vmcnt(27)
	v_cvt_f32_f16_e32 v39, v39
	s_waitcnt vmcnt(26)
	v_cvt_f32_f16_e32 v41, v41
	s_waitcnt vmcnt(25)
	v_cvt_f32_f16_e32 v42, v42
	s_waitcnt vmcnt(24)
	v_cvt_f32_f16_e32 v43, v43
	s_waitcnt vmcnt(23)
	v_cvt_f32_f16_e32 v51, v51
	ds_bpermute_b32 v35, v24, v31
	ds_bpermute_b32 v34, v24, v30
	v_mul_f32_e32 v36, v36, v37
	v_mul_f32_e32 v37, v17, v36
	v_mul_f32_e32 v38, v38, v39
	v_mul_f32_e32 v39, v41, v42
	v_mul_f32_e32 v41, v43, v51
	v_mov_b32_dpp v37, v37 quad_perm:[1,0,3,2] row_mask:0xf bank_mask:0xf bound_ctrl:1
	v_mul_f32_e32 v42, v19, v38
	s_waitcnt lgkmcnt(2)
	v_pk_add_f32 v[28:29], v[28:29], v[32:33]
	v_mul_f32_e32 v43, v21, v39
	v_mul_f32_e32 v51, v23, v41
	v_fmac_f32_e32 v37, v17, v36
	v_mov_b32_dpp v36, v42 quad_perm:[1,0,3,2] row_mask:0xf bank_mask:0xf bound_ctrl:1
	s_waitcnt lgkmcnt(0)
	v_pk_add_f32 v[30:31], v[30:31], v[34:35]
	ds_bpermute_b32 v33, v25, v29
	ds_bpermute_b32 v32, v25, v28
	v_mov_b32_dpp v42, v43 quad_perm:[1,0,3,2] row_mask:0xf bank_mask:0xf bound_ctrl:1
	v_mov_b32_dpp v43, v51 quad_perm:[1,0,3,2] row_mask:0xf bank_mask:0xf bound_ctrl:1
	v_fmac_f32_e32 v36, v19, v38
	ds_bpermute_b32 v35, v25, v31
	ds_bpermute_b32 v34, v25, v30
	v_add_f32_dpp v37, v37, v37 quad_perm:[2,3,0,1] row_mask:0xf bank_mask:0xf bound_ctrl:1
	v_fmac_f32_e32 v42, v21, v39
	v_fmac_f32_e32 v43, v23, v41
	v_add_f32_dpp v36, v36, v36 quad_perm:[2,3,0,1] row_mask:0xf bank_mask:0xf bound_ctrl:1
	v_add_f32_dpp v37, v37, v37 row_half_mirror row_mask:0xf bank_mask:0xf bound_ctrl:1
	v_add_f32_dpp v38, v42, v42 quad_perm:[2,3,0,1] row_mask:0xf bank_mask:0xf bound_ctrl:1
	v_add_f32_dpp v39, v43, v43 quad_perm:[2,3,0,1] row_mask:0xf bank_mask:0xf bound_ctrl:1
	v_add_f32_dpp v36, v36, v36 row_half_mirror row_mask:0xf bank_mask:0xf bound_ctrl:1
	v_add_f32_dpp v37, v37, v37 row_mirror row_mask:0xf bank_mask:0xf bound_ctrl:1
	v_add_f32_dpp v38, v38, v38 row_half_mirror row_mask:0xf bank_mask:0xf bound_ctrl:1
	v_add_f32_dpp v39, v39, v39 row_half_mirror row_mask:0xf bank_mask:0xf bound_ctrl:1
	v_add_f32_dpp v36, v36, v36 row_mirror row_mask:0xf bank_mask:0xf bound_ctrl:1
	ds_bpermute_b32 v41, v24, v37
	v_add_f32_dpp v38, v38, v38 row_mirror row_mask:0xf bank_mask:0xf bound_ctrl:1
	v_add_f32_dpp v39, v39, v39 row_mirror row_mask:0xf bank_mask:0xf bound_ctrl:1
	ds_bpermute_b32 v42, v24, v36
	s_waitcnt lgkmcnt(4)
	v_pk_add_f32 v[28:29], v[28:29], v[32:33]
	ds_bpermute_b32 v43, v24, v38
	ds_bpermute_b32 v51, v24, v39
	s_waitcnt lgkmcnt(4)
	v_pk_add_f32 v[30:31], v[30:31], v[34:35]
	v_pk_fma_f32 v[28:29], v[28:29], s[16:17], v[44:45] op_sel_hi:[1,0,1] neg_lo:[1,0,0] neg_hi:[1,0,0]
	v_pk_fma_f32 v[30:31], v[30:31], s[16:17], v[46:47] op_sel_hi:[1,0,1] neg_lo:[1,0,0] neg_hi:[1,0,0]
	v_pk_mul_f32 v[32:33], v[28:29], v[28:29]
	v_pk_mul_f32 v[34:35], v[30:31], v[30:31]
	s_waitcnt lgkmcnt(3)
	v_add_f32_e32 v41, v37, v41
	v_mov_b32_dpp v33, v33 quad_perm:[1,0,3,2] row_mask:0xf bank_mask:0xf bound_ctrl:1
	v_mov_b32_dpp v32, v32 quad_perm:[1,0,3,2] row_mask:0xf bank_mask:0xf bound_ctrl:1
	v_mov_b32_dpp v35, v35 quad_perm:[1,0,3,2] row_mask:0xf bank_mask:0xf bound_ctrl:1
	v_mov_b32_dpp v34, v34 quad_perm:[1,0,3,2] row_mask:0xf bank_mask:0xf bound_ctrl:1
	v_pk_fma_f32 v[32:33], v[28:29], v[28:29], v[32:33]
	s_waitcnt lgkmcnt(2)
	v_add_f32_e32 v42, v36, v42
	v_pk_fma_f32 v[34:35], v[30:31], v[30:31], v[34:35]
	v_mov_b32_dpp v37, v33 quad_perm:[2,3,0,1] row_mask:0xf bank_mask:0xf bound_ctrl:1
	v_mov_b32_dpp v36, v32 quad_perm:[2,3,0,1] row_mask:0xf bank_mask:0xf bound_ctrl:1
	s_waitcnt lgkmcnt(1)
	v_add_f32_e32 v43, v38, v43
	s_waitcnt lgkmcnt(0)
	v_add_f32_e32 v45, v39, v51
	v_mov_b32_dpp v39, v35 quad_perm:[2,3,0,1] row_mask:0xf bank_mask:0xf bound_ctrl:1
	v_mov_b32_dpp v38, v34 quad_perm:[2,3,0,1] row_mask:0xf bank_mask:0xf bound_ctrl:1
	v_pk_add_f32 v[32:33], v[32:33], v[36:37]
	v_pk_add_f32 v[34:35], v[34:35], v[38:39]
	ds_bpermute_b32 v44, v25, v41
	v_mov_b32_dpp v37, v33 row_half_mirror row_mask:0xf bank_mask:0xf bound_ctrl:1
	v_mov_b32_dpp v36, v32 row_half_mirror row_mask:0xf bank_mask:0xf bound_ctrl:1
	v_mov_b32_dpp v39, v35 row_half_mirror row_mask:0xf bank_mask:0xf bound_ctrl:1
	v_mov_b32_dpp v38, v34 row_half_mirror row_mask:0xf bank_mask:0xf bound_ctrl:1
	v_pk_add_f32 v[32:33], v[32:33], v[36:37]
	v_pk_add_f32 v[34:35], v[34:35], v[38:39]
	ds_bpermute_b32 v46, v25, v42
	v_mov_b32_dpp v37, v33 row_mirror row_mask:0xf bank_mask:0xf bound_ctrl:1
	v_mov_b32_dpp v36, v32 row_mirror row_mask:0xf bank_mask:0xf bound_ctrl:1
	v_mov_b32_dpp v39, v35 row_mirror row_mask:0xf bank_mask:0xf bound_ctrl:1
	v_mov_b32_dpp v38, v34 row_mirror row_mask:0xf bank_mask:0xf bound_ctrl:1
	v_pk_add_f32 v[32:33], v[32:33], v[36:37]
	v_pk_add_f32 v[34:35], v[34:35], v[38:39]
	ds_bpermute_b32 v37, v24, v33
	ds_bpermute_b32 v36, v24, v32
	ds_bpermute_b32 v39, v24, v35
	ds_bpermute_b32 v38, v24, v34
	ds_bpermute_b32 v47, v25, v43
	ds_bpermute_b32 v51, v25, v45
	s_waitcnt lgkmcnt(4)
	v_pk_add_f32 v[32:33], v[32:33], v[36:37]
	ds_bpermute_b32 v37, v25, v33
	s_waitcnt lgkmcnt(3)
	v_pk_add_f32 v[34:35], v[34:35], v[38:39]
	ds_bpermute_b32 v36, v25, v32
	ds_bpermute_b32 v39, v25, v35
	ds_bpermute_b32 v38, v25, v34
	v_add_f32_e32 v41, v41, v44
	v_add_f32_e32 v42, v42, v46
	s_waitcnt lgkmcnt(2)
	v_pk_add_f32 v[32:33], v[32:33], v[36:37]
	v_add_f32_e32 v43, v43, v47
	s_waitcnt lgkmcnt(0)
	v_pk_add_f32 v[34:35], v[34:35], v[38:39]
	v_pk_fma_f32 v[32:33], v[32:33], s[16:17], v[12:13] op_sel_hi:[1,0,0]
	v_pk_fma_f32 v[34:35], v[34:35], s[16:17], v[12:13] op_sel_hi:[1,0,0]
	v_mul_f32_e32 v36, 0x4b800000, v33
	v_cmp_gt_f32_e64 s[8:9], s3, v33
	v_mul_f32_e32 v37, 0x4b800000, v32
	v_cmp_gt_f32_e32 vcc, s3, v32
	v_mul_f32_e32 v38, 0x4b800000, v35
	v_mul_f32_e32 v39, 0x4b800000, v34
	v_cmp_gt_f32_e64 s[4:5], s3, v34
	v_cmp_gt_f32_e64 s[6:7], s3, v35
	v_cndmask_b32_e64 v33, v33, v36, s[8:9]
	v_cndmask_b32_e32 v32, v32, v37, vcc
	v_cndmask_b32_e64 v35, v35, v38, s[6:7]
	v_cndmask_b32_e64 v34, v34, v39, s[4:5]
	v_rsq_f32_e32 v33, v33
	v_rsq_f32_e32 v32, v32
	v_rsq_f32_e32 v35, v35
	v_rsq_f32_e32 v34, v34
	v_mul_f32_e32 v36, 0x45800000, v33
	v_mul_f32_e32 v37, 0x45800000, v32
	v_mul_f32_e32 v38, 0x45800000, v35
	v_mul_f32_e32 v39, 0x45800000, v34
	v_cndmask_b32_e64 v33, v33, v36, s[8:9]
	v_cndmask_b32_e32 v32, v32, v37, vcc
	v_cndmask_b32_e64 v35, v35, v38, s[6:7]
	v_cndmask_b32_e64 v34, v34, v39, s[4:5]
	v_mul_f32_e32 v29, v29, v33
	v_mul_f32_e32 v28, v28, v32
	v_mul_f32_e32 v31, v31, v35
	v_mul_f32_e32 v30, v30, v34
	v_fma_f32 v29, v16, v29, v1
	v_add_f32_e32 v44, v45, v51
	v_fma_f32 v28, v18, v28, v3
	v_fma_f32 v31, v20, v31, v5
	v_fma_f32 v30, v22, v30, v7
	v_fma_mix_f32 v29, v41, v40, v29 op_sel_hi:[0,1,0]
	s_waitcnt vmcnt(22)
	v_fma_mix_f32 v28, v42, v52, v28 op_sel_hi:[0,1,0]
	s_waitcnt vmcnt(21)
	v_fma_mix_f32 v31, v43, v53, v31 op_sel_hi:[0,1,0]
	s_waitcnt vmcnt(20)
	v_fma_mix_f32 v30, v44, v54, v30 op_sel_hi:[0,1,0]
	v_mul_f32_e32 v27, v29, v27
	v_mul_f32_e32 v28, v28, v48
	v_mul_f32_e32 v29, v31, v49
	v_mul_f32_e32 v30, v30, v50
	v_bfe_u32 v31, v27, 16, 1
	v_bfe_u32 v32, v28, 16, 1
	v_bfe_u32 v33, v29, 16, 1
	v_bfe_u32 v34, v30, 16, 1
	v_add3_u32 v27, v27, v31, s17
	v_add3_u32 v28, v28, v32, s17
	v_add3_u32 v29, v29, v33, s17
	v_add3_u32 v30, v30, v34, s17
	global_store_short_d16_hi v[14:15], v27, off offset:1024
	global_store_short_d16_hi v[14:15], v28, off offset:1152
	global_store_short_d16_hi v[14:15], v29, off offset:1280
	global_store_short_d16_hi v[14:15], v30, off offset:1408
	s_cbranch_scc1 .LBB0_1148
